# GEMM epilogues: waves 4-7 (the phase-lagging half) raised to s_setprio 1 from epilogue entry until the next unit's first MMA flip
# baseline (speedup 1.0000x reference)
; #define PG8_BAR __builtin_amdgcn_s_barrier()
; template <class Epi, class Sched, bool ALIGN_EPI = false, bool SP2 = false>
; __device__ __forceinline__ void gemm_phase(PG8_LAS unsigned char* lds, const Gemm g, const Sched& S, const Epi& E, const int wave0) {
;     ...
;         if constexpr (ALIGN_EPI) { if (wr == 0) PG8_BAR; }
;         if constexpr (!Epi::AFTER_DRAIN) { E(acc, cur, wr, wc, fr, fq); S.done(cur); }
.LBB0_319:
	v_readlane_b32 s100, v251, 40
	s_nop 0
	s_bitcmp1_b32 s100, 10
	s_cbranch_scc0 .Lprio_e0
	s_setprio 1
